# attention QK: dead per-tile K address computations removed after the read-ahead change
# speedup vs baseline: 1.0008x; 1.0008x over previous
; #define LAS __attribute__((address_space(3)))
; __device__ __forceinline__ void attn_compute(const MixCtx& X, int a, LAS unsigned char* lds, int tid, const bf16x8 q0, const bf16x8 q1) {
;     const int lane = tid & 63, w = __builtin_amdgcn_readfirstlane(tid >> 6);
;     const int b = a / 96, rem = a % 96, h = rem >> 4, u16 = rem & 15;
;     const int sh = 2 * (h >> 1), dil = 1 << sh, nbm = (16 >> sh) - 1;
;     const int r = u16 >> (4 - sh), n = u16 & nbm;
;     const float slope = exp2f(-8.0f * (float)(h + 1) / 6.0f);
;     const float c1 = 0.125f * LOG2E, c2 = slope * (float)dil * LOG2E;
;     LAS unsigned char* Kl = lds; LAS unsigned char* Vl = lds + 39168;
;     const int j = lane & 15, kq = lane >> 4;
;     const int qi = 16 * w + j; const int qpos = (n * 128 + qi) * dil + r;
;     float s[9][4]; float mx = -1e30f;
;     const int d0 = j + 128 - 4 * kq;
;     float be[4]; const float bstep = 16.0f * c2;
; #pragma unroll
;     for (int e = 0; e < 4; ++e) be[e] = -c2 * (float)(d0 - e);
;     const int nlive0 = (n == 0) ? (8 - w) : 0;
; #pragma unroll
;     for (int tt = 0; tt < 9; ++tt) {
;         if (tt >= nlive0) {
;             const int kt = w + tt; const LAS unsigned char* p = Kl + (16 * kt + j) * 144 + kq * 16;
;             const bf16x8 k0f = *(const LAS bf16x8*)p, k1f = *(const LAS bf16x8*)(p + 64);
;             f32x4 acc = (f32x4){0.f, 0.f, 0.f, 0.f};
;             acc = __builtin_amdgcn_mfma_f32_16x16x32_bf16(k0f, q0, acc, 0, 0, 0);
;             acc = __builtin_amdgcn_mfma_f32_16x16x32_bf16(k1f, q1, acc, 0, 0, 0);
; #pragma unroll
;             for (int e = 0; e < 4; ++e) {
;                 float v = acc[e] * c1 + (be[e] + bstep * (float)tt);
;                 if (tt == 0) { if (d0 - e > 128) v = -1e30f; }
;                 if (tt == 8) { if (d0 - 128 - e < 0) v = -1e30f; }
;                 s[tt][e] = v; mx = fmaxf(mx, v); }
.LBB0_233:
	v_readfirstlane_b32 s4, v67
	s_ashr_i32 s93, s4, 6
	s_mul_hi_i32 s4, s2, 0x2aaaaaab
	s_lshr_b32 s5, s4, 31
	s_ashr_i32 s4, s4, 4
	s_add_i32 s92, s4, s5
	s_mul_i32 s4, s92, 0xffffffa0
	s_add_i32 s4, s2, s4
	s_ashr_i32 s68, s4, 4
	s_add_i32 s5, s68, 1
	v_cvt_f32_i32_e32 v1, s5
	s_and_b32 s63, s68, -2
	s_lshr_b32 s5, 16, s63
	s_and_b32 s4, s4, 15
	v_mul_f32_e32 v1, 0xc1000000, v1
	v_div_scale_f32 v2, s[6:7], s9, s9, v1
	v_rcp_f32_e32 v3, v2
	s_mov_b32 s6, 0xc2fc0000
	s_add_i32 s5, s5, -1
	s_lshl_b32 s26, 1, s63
	v_fma_f32 v52, -v2, v3, 1.0
	v_fmac_f32_e32 v3, v52, v3
	v_div_scale_f32 v52, vcc, v1, s9, v1
	v_mul_f32_e32 v53, v52, v3
	v_fma_f32 v54, -v2, v53, v52
	v_fmac_f32_e32 v53, v54, v3
	v_fma_f32 v2, -v2, v53, v52
	v_div_fmas_f32 v2, v2, v3, v53
	v_div_fixup_f32 v1, v2, s9, v1
	v_cmp_gt_f32_e32 vcc, s6, v1
	v_mov_b32_e32 v2, 0x42800000
	s_and_b32 s5, s5, s4
	v_cndmask_b32_e32 v2, 0, v2, vcc
	v_add_f32_e32 v1, v1, v2
	v_exp_f32_e32 v1, v1
	v_cvt_f32_u32_e32 v2, s26
	s_and_b64 s[6:7], vcc, exec
	s_cselect_b32 s6, 0xffffffc0, 0
	v_ldexp_f32 v1, v1, s6
	s_lshl_b32 s69, s93, 4
	s_sub_i32 s6, 8, s93
	s_cmp_eq_u32 s5, 0
	v_mul_f32_e32 v1, v1, v2
	s_cselect_b32 s6, s6, 0
	v_mul_f32_e32 v2, 0x3fb8aa3b, v1
	s_cmp_lt_i32 s6, 1
	v_pk_mul_f32 v[56:57], v[2:3], v[62:63] op_sel_hi:[0,1] neg_lo:[1,0] neg_hi:[1,0]
	v_pk_mul_f32 v[52:53], v[2:3], v[64:65] op_sel_hi:[0,1] neg_lo:[1,0] neg_hi:[1,0]
	v_mul_f32_e32 v58, 0x41800000, v2
	v_mov_b32_e32 v2, 0xf149f2ca
	s_cselect_b64 s[54:55], -1, 0
	s_cmp_gt_i32 s6, 0
	v_mov_b32_e32 v73, 0xf149f2ca
	v_mov_b32_e32 v75, 0xf149f2ca
	v_mov_b32_e32 v132, 0xf149f2ca
	v_mov_b32_e32 v59, 0xf149f2ca
	v_mov_b32_e32 v1, 0xf149f2ca
	v_or_b32_e32 v184, s69, v103
	v_mul_u32_u24_e32 v184, 0x90, v184
	v_add_u32_e32 v184, v184, v66
	ds_read_b128 v[192:195], v184
	ds_read_b128 v[196:199], v184 offset:64
	ds_read_b128 v[200:203], v184 offset:2304
	ds_read_b128 v[204:207], v184 offset:2368
	ds_read_b128 v[208:211], v184 offset:4608
	ds_read_b128 v[212:215], v184 offset:4672
	ds_read_b128 v[216:219], v184 offset:6912
	ds_read_b128 v[220:223], v184 offset:6976
	ds_read_b128 v[224:227], v184 offset:9216
	ds_read_b128 v[228:231], v184 offset:9280
	ds_read_b128 v[162:165], v184 offset:11520
	ds_read_b128 v[166:169], v184 offset:11584
	ds_read_b128 v[170:173], v184 offset:13824
	ds_read_b128 v[180:183], v184 offset:13888
	s_cbranch_scc1 .LBB0_235
	v_mul_f32_e32 v54, 0, v58
	s_mov_b32 s7, 0xf149f2ca
	s_waitcnt lgkmcnt(13)
	v_mfma_f32_16x16x32_bf16 v[76:79], v[192:195], v[48:51], 0
	s_waitcnt lgkmcnt(12)
	v_mfma_f32_16x16x32_bf16 v[76:79], v[196:199], v[44:47], v[76:79]
	v_add_f32_e64 v80, v56, v54
	v_add_f32_e64 v81, v57, v54
	v_pk_add_f32 v[54:55], v[52:53], v[54:55] op_sel_hi:[1,0]
	s_nop 4
	v_pk_fma_f32 v[76:77], v[76:77], s[72:73], v[80:81] op_sel_hi:[1,0,1]
	v_pk_fma_f32 v[54:55], v[78:79], s[72:73], v[54:55] op_sel_hi:[1,0,1]
	v_cndmask_b32_e64 v59, v76, v178, s[38:39]
	v_cndmask_b32_e64 v1, v77, v178, s[36:37]
	v_max3_f32 v3, v59, s7, v1
	v_cndmask_b32_e64 v75, v54, v178, s[42:43]
	v_cndmask_b32_e64 v132, v55, v178, s[40:41]
	v_max3_f32 v73, v3, v75, v132
.LBB0_235:
	ds_read_b128 v[192:195], v184 offset:16128
	ds_read_b128 v[196:199], v184 offset:16192
	s_cmp_lt_i32 s6, 2
	s_cselect_b64 s[56:57], -1, 0
	s_cmp_gt_i32 s6, 1
	s_cbranch_scc1 .LBB0_237
	v_pk_add_f32 v[2:3], v[58:59], v[56:57] op_sel_hi:[0,1]
	v_pk_add_f32 v[54:55], v[58:59], v[52:53] op_sel_hi:[0,1]
	s_waitcnt lgkmcnt(13)
	v_mfma_f32_16x16x32_bf16 v[76:79], v[200:203], v[48:51], 0
	s_waitcnt lgkmcnt(12)
	v_mfma_f32_16x16x32_bf16 v[76:79], v[204:207], v[44:47], v[76:79]
	s_nop 7
	v_pk_fma_f32 v[76:77], v[76:77], s[72:73], v[2:3] op_sel_hi:[1,0,1]
	v_pk_fma_f32 v[2:3], v[78:79], s[72:73], v[54:55] op_sel_hi:[1,0,1]
	v_max3_f32 v73, v73, v76, v77
	v_max3_f32 v73, v73, v2, v3
	s_branch .LBB0_238

; #define LAS __attribute__((address_space(3)))
; __device__ __forceinline__ void attn_compute(const MixCtx& X, int a, LAS unsigned char* lds, int tid, const bf16x8 q0, const bf16x8 q1) {
;     ...
;     for (int tt = 0; tt < 9; ++tt) {
;         if (tt >= nlive0) {
;             const int kt = w + tt; const LAS unsigned char* p = Kl + (16 * kt + j) * 144 + kq * 16;
;             const bf16x8 k0f = *(const LAS bf16x8*)p, k1f = *(const LAS bf16x8*)(p + 64);
;             f32x4 acc = (f32x4){0.f, 0.f, 0.f, 0.f};
;             acc = __builtin_amdgcn_mfma_f32_16x16x32_bf16(k0f, q0, acc, 0, 0, 0);
;             acc = __builtin_amdgcn_mfma_f32_16x16x32_bf16(k1f, q1, acc, 0, 0, 0);
; #pragma unroll
;             for (int e = 0; e < 4; ++e) {
;                 float v = acc[e] * c1 + (be[e] + bstep * (float)tt);
;                 if (tt == 0) { if (d0 - e > 128) v = -1e30f; }
;                 if (tt == 8) { if (d0 - 128 - e < 0) v = -1e30f; }
;                 s[tt][e] = v; mx = fmaxf(mx, v); }
.LBB0_238:
	ds_read_b128 v[200:203], v184 offset:18432
	ds_read_b128 v[204:207], v184 offset:18496
	s_cmp_lt_i32 s6, 3
	s_cselect_b64 s[58:59], -1, 0
	s_cmp_gt_i32 s6, 2
	v_mov_b32_e32 v54, 0xf149f2ca
	s_cbranch_scc1 .LBB0_241
	s_waitcnt lgkmcnt(13)
	v_mfma_f32_16x16x32_bf16 v[78:81], v[208:211], v[48:51], 0
	s_waitcnt lgkmcnt(12)
	v_mfma_f32_16x16x32_bf16 v[78:81], v[212:215], v[44:47], v[78:81]
	v_add_f32_e32 v82, v58, v58
	v_pk_add_f32 v[84:85], v[56:57], v[82:83] op_sel_hi:[1,0]
	v_pk_add_f32 v[82:83], v[52:53], v[82:83] op_sel_hi:[1,0]
	s_nop 4
	v_pk_fma_f32 v[78:79], v[78:79], s[72:73], v[84:85] op_sel_hi:[1,0,1]
	v_pk_fma_f32 v[80:81], v[80:81], s[72:73], v[82:83] op_sel_hi:[1,0,1]
	v_max3_f32 v55, v73, v78, v79
	v_max3_f32 v73, v55, v80, v81
	s_cmp_lt_i32 s6, 4
	s_cselect_b64 s[26:27], -1, 0
	s_cmp_gt_i32 s6, 3
	s_cbranch_scc0 .LBB0_242

; #define LAS __attribute__((address_space(3)))
; __device__ __forceinline__ void attn_compute(const MixCtx& X, int a, LAS unsigned char* lds, int tid, const bf16x8 q0, const bf16x8 q1) {
;     ...
;     for (int tt = 0; tt < 9; ++tt) {
;         if (tt >= nlive0) {
;             const int kt = w + tt; const LAS unsigned char* p = Kl + (16 * kt + j) * 144 + kq * 16;
;             const bf16x8 k0f = *(const LAS bf16x8*)p, k1f = *(const LAS bf16x8*)(p + 64);
;             f32x4 acc = (f32x4){0.f, 0.f, 0.f, 0.f};
;             acc = __builtin_amdgcn_mfma_f32_16x16x32_bf16(k0f, q0, acc, 0, 0, 0);
;             acc = __builtin_amdgcn_mfma_f32_16x16x32_bf16(k1f, q1, acc, 0, 0, 0);
; #pragma unroll
;             for (int e = 0; e < 4; ++e) {
;                 float v = acc[e] * c1 + (be[e] + bstep * (float)tt);
;                 if (tt == 0) { if (d0 - e > 128) v = -1e30f; }
;                 if (tt == 8) { if (d0 - 128 - e < 0) v = -1e30f; }
;                 s[tt][e] = v; mx = fmaxf(mx, v); }
.LBB0_242:
	v_mul_f32_e32 v54, 0x40400000, v58
	s_waitcnt lgkmcnt(11)
	v_mfma_f32_16x16x32_bf16 v[82:85], v[216:219], v[48:51], 0
	s_waitcnt lgkmcnt(10)
	v_mfma_f32_16x16x32_bf16 v[82:85], v[220:223], v[44:47], v[82:85]
	v_add_f32_e64 v86, v56, v54
	v_add_f32_e64 v87, v57, v54
	v_pk_add_f32 v[54:55], v[52:53], v[54:55] op_sel_hi:[1,0]
	s_nop 4
	v_pk_fma_f32 v[82:83], v[82:83], s[72:73], v[86:87] op_sel_hi:[1,0,1]
	v_pk_fma_f32 v[54:55], v[84:85], s[72:73], v[54:55] op_sel_hi:[1,0,1]
	v_max3_f32 v73, v73, v82, v83
	v_max3_f32 v73, v73, v54, v55
.LBB0_243:
	s_cmp_lt_i32 s6, 5
	s_cselect_b64 s[78:79], -1, 0
	s_cmp_gt_i32 s6, 4
	v_mov_b32_e32 v84, 0xf149f2ca
	s_cbranch_scc1 .LBB0_246
	s_waitcnt lgkmcnt(9)
	v_mfma_f32_16x16x32_bf16 v[86:89], v[224:227], v[48:51], 0
	s_waitcnt lgkmcnt(8)
	v_mfma_f32_16x16x32_bf16 v[86:89], v[228:231], v[44:47], v[86:89]
	v_mul_f32_e32 v90, 4.0, v58
	v_pk_add_f32 v[92:93], v[56:57], v[90:91] op_sel_hi:[1,0]
	v_pk_add_f32 v[90:91], v[52:53], v[90:91] op_sel_hi:[1,0]
	s_nop 4
	v_pk_fma_f32 v[86:87], v[86:87], s[72:73], v[92:93] op_sel_hi:[1,0,1]
	v_pk_fma_f32 v[88:89], v[88:89], s[72:73], v[90:91] op_sel_hi:[1,0,1]
	v_max3_f32 v73, v73, v86, v87
	v_max3_f32 v73, v73, v88, v89
	s_cmp_lt_i32 s6, 6
	s_cselect_b64 s[82:83], -1, 0
	s_cmp_gt_i32 s6, 5
	s_cbranch_scc0 .LBB0_247

; #define LAS __attribute__((address_space(3)))
; __device__ __forceinline__ void attn_compute(const MixCtx& X, int a, LAS unsigned char* lds, int tid, const bf16x8 q0, const bf16x8 q1) {
;     ...
;     for (int tt = 0; tt < 9; ++tt) {
;         if (tt >= nlive0) {
;             const int kt = w + tt; const LAS unsigned char* p = Kl + (16 * kt + j) * 144 + kq * 16;
;             const bf16x8 k0f = *(const LAS bf16x8*)p, k1f = *(const LAS bf16x8*)(p + 64);
;             f32x4 acc = (f32x4){0.f, 0.f, 0.f, 0.f};
;             acc = __builtin_amdgcn_mfma_f32_16x16x32_bf16(k0f, q0, acc, 0, 0, 0);
;             acc = __builtin_amdgcn_mfma_f32_16x16x32_bf16(k1f, q1, acc, 0, 0, 0);
; #pragma unroll
;             for (int e = 0; e < 4; ++e) {
;                 float v = acc[e] * c1 + (be[e] + bstep * (float)tt);
;                 if (tt == 0) { if (d0 - e > 128) v = -1e30f; }
;                 if (tt == 8) { if (d0 - 128 - e < 0) v = -1e30f; }
;                 s[tt][e] = v; mx = fmaxf(mx, v); }
.LBB0_247:
	v_mul_f32_e32 v84, 0x40a00000, v58
	s_waitcnt lgkmcnt(7)
	v_mfma_f32_16x16x32_bf16 v[90:93], v[162:165], v[48:51], 0
	s_waitcnt lgkmcnt(6)
	v_mfma_f32_16x16x32_bf16 v[90:93], v[166:169], v[44:47], v[90:93]
	v_add_f32_e64 v94, v56, v84
	v_add_f32_e64 v95, v57, v84
	v_pk_add_f32 v[84:85], v[52:53], v[84:85] op_sel_hi:[1,0]
	s_nop 4
	v_pk_fma_f32 v[90:91], v[90:91], s[72:73], v[94:95] op_sel_hi:[1,0,1]
	v_pk_fma_f32 v[84:85], v[92:93], s[72:73], v[84:85] op_sel_hi:[1,0,1]
	v_max3_f32 v73, v73, v90, v91
	v_max3_f32 v73, v73, v84, v85
.LBB0_248:
	s_cmp_lt_i32 s6, 7
	s_cselect_b64 s[76:77], -1, 0
	s_cmp_gt_i32 s6, 6
	v_mov_b32_e32 v92, 0xf149f2ca
	s_cbranch_scc1 .LBB0_251
	v_mul_f32_e32 v98, 0x40c00000, v58
	s_waitcnt lgkmcnt(5)
	v_mfma_f32_16x16x32_bf16 v[94:97], v[170:173], v[48:51], 0
	s_waitcnt lgkmcnt(4)
	v_mfma_f32_16x16x32_bf16 v[94:97], v[180:183], v[44:47], v[94:97]
	v_add_f32_e64 v134, v56, v98
	v_add_f32_e64 v135, v57, v98
	v_pk_add_f32 v[98:99], v[52:53], v[98:99] op_sel_hi:[1,0]
	s_nop 4
	v_pk_fma_f32 v[94:95], v[94:95], s[72:73], v[134:135] op_sel_hi:[1,0,1]
	v_pk_fma_f32 v[96:97], v[96:97], s[72:73], v[98:99] op_sel_hi:[1,0,1]
	v_max3_f32 v73, v73, v94, v95
	v_max3_f32 v73, v73, v96, v97
	s_cmp_lt_i32 s6, 8
	s_cselect_b64 s[80:81], -1, 0
	s_cmp_gt_i32 s6, 7
	s_cbranch_scc0 .LBB0_252

; #define LAS __attribute__((address_space(3)))
; __device__ __forceinline__ void attn_compute(const MixCtx& X, int a, LAS unsigned char* lds, int tid, const bf16x8 q0, const bf16x8 q1) {
;     ...
;     for (int tt = 0; tt < 9; ++tt) {
;         if (tt >= nlive0) {
;             const int kt = w + tt; const LAS unsigned char* p = Kl + (16 * kt + j) * 144 + kq * 16;
;             const bf16x8 k0f = *(const LAS bf16x8*)p, k1f = *(const LAS bf16x8*)(p + 64);
;             f32x4 acc = (f32x4){0.f, 0.f, 0.f, 0.f};
;             acc = __builtin_amdgcn_mfma_f32_16x16x32_bf16(k0f, q0, acc, 0, 0, 0);
;             acc = __builtin_amdgcn_mfma_f32_16x16x32_bf16(k1f, q1, acc, 0, 0, 0);
; #pragma unroll
;             for (int e = 0; e < 4; ++e) {
;                 float v = acc[e] * c1 + (be[e] + bstep * (float)tt);
;                 if (tt == 0) { if (d0 - e > 128) v = -1e30f; }
;                 if (tt == 8) { if (d0 - 128 - e < 0) v = -1e30f; }
;                 s[tt][e] = v; mx = fmaxf(mx, v); }
.LBB0_252:
	v_mul_f32_e32 v92, 0x40e00000, v58
	v_pk_add_f32 v[98:99], v[56:57], v[92:93] op_sel_hi:[1,0]
	s_waitcnt lgkmcnt(3)
	v_mfma_f32_16x16x32_bf16 v[134:137], v[192:195], v[48:51], 0
	v_pk_add_f32 v[92:93], v[52:53], v[92:93] op_sel_hi:[1,0]
	s_waitcnt lgkmcnt(2)
	v_mfma_f32_16x16x32_bf16 v[134:137], v[196:199], v[44:47], v[134:137]
	s_nop 7
	v_pk_fma_f32 v[98:99], v[134:135], s[72:73], v[98:99] op_sel_hi:[1,0,1]
	v_pk_fma_f32 v[92:93], v[136:137], s[72:73], v[92:93] op_sel_hi:[1,0,1]
	v_max3_f32 v73, v73, v98, v99
	v_max3_f32 v73, v73, v92, v93
.LBB0_253:
	s_cmp_lt_i32 s6, 9
	s_cselect_b64 s[84:85], -1, 0
	s_cmp_gt_i32 s6, 8
	v_mov_b32_e32 v134, 0xf149f2ca
	s_cbranch_scc1 .LBB0_255
	v_mul_f32_e32 v58, 0x41000000, v58
	v_pk_add_f32 v[56:57], v[56:57], v[58:59] op_sel_hi:[1,0]
	s_waitcnt lgkmcnt(1)
	v_mfma_f32_16x16x32_bf16 v[48:51], v[200:203], v[48:51], 0
	v_add_f32_e64 v52, v52, v58
	v_add_f32_e64 v53, v53, v58
	s_waitcnt lgkmcnt(0)
	v_mfma_f32_16x16x32_bf16 v[44:47], v[204:207], v[44:47], v[48:51]
	s_nop 7
	v_pk_fma_f32 v[44:45], v[44:45], s[72:73], v[56:57] op_sel_hi:[1,0,1]
	v_pk_fma_f32 v[48:49], v[46:47], s[72:73], v[52:53] op_sel_hi:[1,0,1]
	v_cndmask_b32_e64 v134, v44, v178, s[46:47]
	v_cndmask_b32_e64 v47, v45, v178, s[44:45]
	v_cndmask_b32_e64 v45, v48, v178, s[50:51]
	v_max3_f32 v44, v73, v134, v47
	v_cndmask_b32_e64 v46, v49, v178, s[48:49]
	v_max3_f32 v73, v44, v45, v46
	s_branch .LBB0_256
